# conv in-proj: per-row rsqrt scales computed once per WG and kept in spare VGPRs across its three tiles
# speedup vs baseline: 1.1169x; 1.0001x over previous
; __device__ __forceinline__ void row_rs8(const float* ssq, int row0, int fq, float (&rr)[2][4]) {
;     float v[2][4][4];
; #pragma unroll
;     for (int ai = 0; ai < 2; ++ai)
; #pragma unroll
;         for (int m = 0; m < 4; ++m) { const float* p = ssq + (size_t)(4 * fq) * 16384 + row0 + ai * HALF + m * 16;
; #pragma unroll
;             for (int k = 0; k < 4; ++k) v[ai][m][k] = ld_agent(p + k * 16384); }
; #pragma unroll
;     for (int ai = 0; ai < 2; ++ai)
; #pragma unroll
;         for (int m = 0; m < 4; ++m) { float s = (v[ai][m][0] + v[ai][m][1]) + (v[ai][m][2] + v[ai][m][3]);
;             s += __shfl_xor(s, 16); s += __shfl_xor(s, 32); rr[ai][m] = __builtin_amdgcn_rsqf(s * (1.0f / 1024.0f) + RMS_EPS); }
; }
;     __device__ __forceinline__ void operator()(const f32x4 (&acc)[2][2][4][2], const Unit& u, int wr, int wc, int fr, int fq) const {
;         const int row0 = u.pm * BM + wr * 64 + fr; float rr[2][4]; row_rs8(ssq, row0, fq, rr);
;         if (u.pn < 8) {
.LBB0_291:
	v_mov_b32_e32 v130, v248
	v_readlane_b32 s6, v255, 4
	v_readlane_b32 s8, v252, 21
	v_readlane_b32 s9, v252, 22
	v_add_u32_e32 v155, s6, v130
	v_lshl_add_u32 v202, s3, 8, v155
	v_ashrrev_i32_e32 v203, 31, v202
	s_mov_b64 s[6:7], -1
	s_cmp_lt_u32 s37, 4
	s_cbranch_scc1 .Lrr_compute
	v_mov_b32_e32 v192, v226
	v_mov_b32_e32 v198, v227
	v_mov_b32_e32 v196, v228
	v_mov_b32_e32 v194, v229
	v_mov_b32_e32 v190, v230
	v_mov_b32_e32 v188, v231
	v_mov_b32_e32 v186, v232
	v_mov_b32_e32 v184, v233
	s_branch .Lrr_done
.Lrr_compute:
	v_lshl_add_u64 v[130:131], v[202:203], 2, v[178:179]
	s_mov_b32 s6, 0x10000
	v_add_co_u32_e32 v132, vcc, s6, v130
	s_mov_b32 s6, 0x20000
	s_nop 0
	v_addc_co_u32_e32 v133, vcc, 0, v131, vcc
	v_add_co_u32_e32 v134, vcc, s6, v130
	s_mov_b32 s6, 0x30000
	s_nop 0
	v_addc_co_u32_e32 v135, vcc, 0, v131, vcc
	v_add_co_u32_e32 v136, vcc, s6, v130
	s_mov_b64 s[6:7], -1
	s_nop 0
	v_addc_co_u32_e32 v137, vcc, 0, v131, vcc
	global_load_dword v138, v[132:133], off
	global_load_dword v139, v[132:133], off offset:64
	global_load_dword v140, v[132:133], off offset:128
	global_load_dword v141, v[134:135], off
	global_load_dword v142, v[134:135], off offset:64
	global_load_dword v143, v[134:135], off offset:128
	global_load_dword v144, v[134:135], off offset:192
	global_load_dword v145, v[136:137], off
	global_load_dword v146, v[136:137], off offset:64
	global_load_dword v147, v[136:137], off offset:128
	global_load_dword v148, v[136:137], off offset:192
	global_load_dword v149, v[136:137], off offset:512
	global_load_dword v150, v[130:131], off
	global_load_dword v151, v[130:131], off offset:64
	global_load_dword v152, v[130:131], off offset:128
	global_load_dword v153, v[130:131], off offset:192
	global_load_dword v154, v[130:131], off offset:512
	global_load_dword v156, v[130:131], off offset:576
	global_load_dword v157, v[132:133], off offset:192
	global_load_dword v158, v[132:133], off offset:512
	global_load_dword v159, v[132:133], off offset:576
	global_load_dword v160, v[134:135], off offset:512
	global_load_dword v161, v[134:135], off offset:576
	global_load_dword v162, v[136:137], off offset:576
	global_load_dword v163, v[130:131], off offset:640
	global_load_dword v164, v[132:133], off offset:640
	global_load_dword v165, v[134:135], off offset:640
	global_load_dword v168, v[136:137], off offset:640
	s_nop 0
	global_load_dword v130, v[130:131], off offset:704
	s_nop 0
	global_load_dword v131, v[132:133], off offset:704
	s_nop 0
	global_load_dword v132, v[134:135], off offset:704
	global_load_dword v133, v[136:137], off offset:704
	v_and_b32_e32 v135, 64, v242
	v_xor_b32_e32 v134, 16, v242
	v_add_u32_e32 v135, 64, v135
	v_xor_b32_e32 v136, 32, v242
	v_cmp_lt_i32_e32 vcc, v134, v135
	s_cmp_gt_i32 s37, 7
	s_waitcnt vmcnt(0)
	v_add_f32_e32 v137, v141, v145
	v_cndmask_b32_e32 v134, v242, v134, vcc
	v_cmp_lt_i32_e32 vcc, v136, v135
	v_add_f32_e32 v141, v143, v147
	v_lshlrev_b32_e32 v134, 2, v134
	v_cndmask_b32_e32 v135, v242, v136, vcc
	v_add_f32_e32 v136, v150, v138
	v_add_f32_e32 v138, v151, v139
	v_add_f32_e32 v139, v142, v146
	v_add_f32_e32 v140, v152, v140
	v_add_f32_e32 v143, v144, v148
	v_add_f32_e32 v142, v153, v157
	v_add_f32_e32 v136, v136, v137
	v_add_f32_e32 v137, v138, v139
	v_add_f32_e32 v138, v140, v141
	v_add_f32_e32 v144, v154, v158
	v_add_f32_e32 v145, v160, v149
	v_add_f32_e32 v139, v142, v143
	ds_bpermute_b32 v143, v134, v138
	v_add_f32_e32 v140, v144, v145
	ds_bpermute_b32 v141, v134, v136
	ds_bpermute_b32 v142, v134, v137
	ds_bpermute_b32 v144, v134, v139
	ds_bpermute_b32 v145, v134, v140
	v_lshlrev_b32_e32 v135, 2, v135
	s_waitcnt lgkmcnt(0)
	v_add_f32_e32 v138, v138, v143
	v_add_f32_e32 v136, v136, v141
	ds_bpermute_b32 v143, v135, v138
	v_add_f32_e32 v137, v137, v142
	v_add_f32_e32 v139, v139, v144
	v_add_f32_e32 v140, v140, v145
	ds_bpermute_b32 v141, v135, v136
	ds_bpermute_b32 v142, v135, v137
	ds_bpermute_b32 v144, v135, v139
	ds_bpermute_b32 v145, v135, v140
	s_waitcnt lgkmcnt(4)
	v_add_f32_e32 v138, v138, v143
	s_waitcnt lgkmcnt(3)
	v_add_f32_e32 v136, v136, v141
	v_fmamk_f32 v138, v138, 0x3a800000, v1
	v_add_f32_e32 v146, v156, v159
	v_add_f32_e32 v147, v161, v162
	s_waitcnt lgkmcnt(2)
	v_add_f32_e32 v137, v137, v142
	s_waitcnt lgkmcnt(1)
	v_add_f32_e32 v139, v139, v144
	v_fmamk_f32 v136, v136, 0x3a800000, v1
	v_rsq_f32_e32 v192, v138
	s_waitcnt lgkmcnt(0)
	v_add_f32_e32 v138, v140, v145
	v_fmamk_f32 v137, v137, 0x3a800000, v1
	v_fmamk_f32 v139, v139, 0x3a800000, v1
	v_rsq_f32_e32 v198, v136
	v_add_f32_e32 v136, v146, v147
	v_fmamk_f32 v138, v138, 0x3a800000, v1
	v_rsq_f32_e32 v196, v137
	ds_bpermute_b32 v137, v134, v136
	v_rsq_f32_e32 v194, v139
	v_rsq_f32_e32 v190, v138
	v_add_f32_e32 v138, v163, v164
	v_add_f32_e32 v139, v165, v168
	v_add_f32_e32 v130, v130, v131
	v_add_f32_e32 v131, v132, v133
	v_add_f32_e32 v138, v138, v139
	v_add_f32_e32 v130, v130, v131
	ds_bpermute_b32 v139, v134, v138
	ds_bpermute_b32 v131, v134, v130
	s_waitcnt lgkmcnt(2)
	v_add_f32_e32 v136, v136, v137
	ds_bpermute_b32 v137, v135, v136
	s_waitcnt lgkmcnt(2)
	v_add_f32_e32 v133, v138, v139
	s_waitcnt lgkmcnt(1)
	v_add_f32_e32 v130, v130, v131
	ds_bpermute_b32 v134, v135, v133
	ds_bpermute_b32 v131, v135, v130
	s_waitcnt lgkmcnt(2)
	v_add_f32_e32 v132, v136, v137
	v_fmamk_f32 v132, v132, 0x3a800000, v1
	v_rsq_f32_e32 v188, v132
	s_waitcnt lgkmcnt(1)
	v_add_f32_e32 v132, v133, v134
	s_waitcnt lgkmcnt(0)
	v_add_f32_e32 v130, v130, v131
	v_fmamk_f32 v132, v132, 0x3a800000, v1
	v_fmamk_f32 v130, v130, 0x3a800000, v1
	v_rsq_f32_e32 v186, v132
	v_rsq_f32_e32 v184, v130
	s_nop 0
	v_mov_b32_e32 v226, v192
	v_mov_b32_e32 v227, v198
	v_mov_b32_e32 v228, v196
	v_mov_b32_e32 v229, v194
	v_mov_b32_e32 v230, v190
	v_mov_b32_e32 v231, v188
	v_mov_b32_e32 v232, v186
	v_mov_b32_e32 v233, v184
;     __device__ __forceinline__ void operator()(const f32x4 (&acc)[2][2][4][2], const Unit& u, int wr, int wc, int fr, int fq) const {
;     ...
;         } else {
;             asm volatile("s_waitcnt vmcnt(0)" ::: "memory");
; #pragma unroll
;             for (int bj = 0; bj < 2; ++bj) {
;                 const int col = (u.pn - 8) * BM + bj * HALF + wc * 32 + 8 * fq;
;                 const f32x4 k0a = *(const f32x4*)(taps + col), k0b = *(const f32x4*)(taps + col + 4), k1a = *(const f32x4*)(taps + 1024 + col), k1b = *(const f32x4*)(taps + 1024 + col + 4),
;                             k2a = *(const f32x4*)(taps + 2048 + col), k2b = *(const f32x4*)(taps + 2048 + col + 4);
; #pragma unroll
;                 for (int ai = 0; ai < 2; ++ai)
; #pragma unroll
;                     for (int m = 0; m < 4; ++m) { const int row = row0 + ai * HALF + m * 16, sq = row & 8191, lr = row & 255; const float r = rr[ai][m];
;                         const bool up_in = lr != 0, dn_in = lr != 255, up_halo = !up_in && sq != 0, dn_halo = !dn_in && sq != 8191;
;                         const bf16_t* up = U + (size_t)row * 1024 + col; const u32x4 z0 = {0u, 0u, 0u, 0u};
;                         const u32x4 uc = *(const u32x4*)up, ul = up_in ? *(const u32x4*)(up - 1024) : z0, ur = dn_in ? *(const u32x4*)(up + 1024) : z0;
.Lrr_done:
	s_cmp_gt_i32 s37, 7
	v_lshlrev_b64 v[130:131], 11, v[202:203]
	v_lshl_add_u64 v[200:201], s[8:9], 0, v[130:131]
	s_cbranch_scc0 .LBB0_421
	s_lshl_b32 s76, s37, 8
	v_or_b32_e32 v130, 0xfffff800, v250
	v_add_u32_e32 v206, s76, v130
	v_ashrrev_i32_e32 v207, 31, v206
	v_readlane_b32 s6, v255, 11
	v_lshlrev_b64 v[138:139], 2, v[206:207]
	v_readlane_b32 s7, v255, 12
	s_waitcnt vmcnt(0)
	s_barrier
	v_readfirstlane_b32 s101, v0
	s_lshr_b32 s101, s101, 6
	s_lshl_b32 s101, s101, 14
	v_and_b32_e32 v166, 63, v0
	v_lshrrev_b32_e32 v158, 4, v166
	v_and_b32_e32 v166, 15, v166
	v_lshlrev_b32_e32 v166, 6, v166
	v_lshl_add_u32 v166, v158, 4, v166
	v_add_u32_e32 v166, s101, v166
	v_lshl_add_u64 v[204:205], v[206:207], 1, v[200:201]
	v_mov_b32_e32 v154, 0
	v_lshl_add_u64 v[134:135], s[6:7], 0, v[138:139]
	v_readlane_b32 s6, v255, 9
	v_readlane_b32 s7, v255, 10
	global_load_dwordx4 v[130:133], v[134:135], off offset:16
	global_load_dwordx4 v[150:153], v[134:135], off
	v_lshl_add_u64 v[140:141], s[6:7], 0, v[138:139]
	v_readlane_b32 s6, v255, 13
	v_readlane_b32 s7, v255, 14
	global_load_dwordx4 v[134:137], v[140:141], off offset:16
	global_load_dwordx4 v[146:149], v[140:141], off
	v_lshl_add_u64 v[142:143], s[6:7], 0, v[138:139]
	global_load_dwordx4 v[138:141], v[142:143], off offset:16
	s_nop 0
	global_load_dwordx4 v[142:145], v[142:143], off
	v_cmp_eq_u32_sdwa s[10:11], v155, v167 src0_sel:BYTE_0 src1_sel:DWORD
	v_and_b32_e32 v158, 63, v0
	v_and_b32_e32 v159, 15, v158
	v_lshrrev_b32_e32 v160, 4, v158
	v_lshrrev_b32_e32 v161, 2, v159
	v_lshl_add_u32 v161, v160, 2, v161
	v_sub_u32_e32 v161, v161, v159
	v_add_u32_e32 v161, -1, v161
	v_lshlrev_b32_e32 v161, 11, v161
	v_and_b32_e32 v159, 3, v159
	v_sub_u32_e32 v159, v159, v160
	v_lshl_add_u32 v162, v159, 4, v161
	v_ashrrev_i32_e32 v163, 31, v162
	v_lshl_add_u64 v[162:163], v[204:205], 0, v[162:163]
	v_lshrrev_b32_e32 v160, 3, v158
	v_min_u32_e32 v160, 1, v160
	v_mul_u32_u24_e32 v160, 0x1f000, v160
	v_mov_b32_e32 v161, 0
	v_mov_b32_e32 v159, 0
	s_mov_b32 m0, s101
	s_nop 0
	global_load_lds_dwordx4 v[162:163], off
	s_add_i32 m0, s101, 0x400
	v_mov_b32_e32 v158, 0x8000
	v_lshl_add_u64 v[164:165], v[162:163], 0, v[158:159]
	global_load_lds_dwordx4 v[164:165], off
	s_add_i32 m0, s101, 0x800
	v_mov_b32_e32 v158, 0x10000
	v_lshl_add_u64 v[164:165], v[162:163], 0, v[158:159]
	global_load_lds_dwordx4 v[164:165], off
	s_add_i32 m0, s101, 0xc00
	v_mov_b32_e32 v158, 0x18000
	v_lshl_add_u64 v[164:165], v[162:163], 0, v[158:159]
	global_load_lds_dwordx4 v[164:165], off
	s_add_i32 m0, s101, 0x1000
	v_mov_b32_e32 v158, 0x20000
	v_lshl_add_u64 v[164:165], v[162:163], 0, v[158:159]
	v_lshl_add_u64 v[164:165], v[164:165], 0, v[160:161]
	global_load_lds_dwordx4 v[164:165], off
	s_add_i32 m0, s101, 0x1400
	v_mov_b32_e32 v158, 0x47000
	v_lshl_add_u64 v[164:165], v[162:163], 0, v[158:159]
	global_load_lds_dwordx4 v[164:165], off
	s_add_i32 m0, s101, 0x1800
	v_mov_b32_e32 v158, 0x4f000
	v_lshl_add_u64 v[164:165], v[162:163], 0, v[158:159]
	global_load_lds_dwordx4 v[164:165], off
	s_add_i32 m0, s101, 0x1c00
	v_mov_b32_e32 v158, 0x57000
	v_lshl_add_u64 v[164:165], v[162:163], 0, v[158:159]
	global_load_lds_dwordx4 v[164:165], off
	s_add_i32 m0, s101, 0x2000
	v_mov_b32_e32 v158, 0x5f000
	v_lshl_add_u64 v[164:165], v[162:163], 0, v[158:159]
	global_load_lds_dwordx4 v[164:165], off
	s_waitcnt vmcnt(0)
	s_barrier
	v_mov_b32_e32 v162, 0
	v_mov_b32_e32 v163, 0
	v_mov_b32_e32 v164, 0
	v_mov_b32_e32 v165, 0
	ds_read_b128 v[158:161], v166 offset:64
	v_cmp_ne_u32_sdwa s[6:7], v155, v167 src0_sel:BYTE_0 src1_sel:DWORD
	v_mov_b32_e32 v162, 0
	v_mov_b32_e32 v163, 0
	v_mov_b32_e32 v164, 0
	v_mov_b32_e32 v165, 0
	s_and_saveexec_b64 s[8:9], s[6:7]
	s_cbranch_execz .LBB0_294
	ds_read_b128 v[162:165], v166 offset:0
